# GEMM unit start: 128 v_mov_b32 accumulator zeroing replaced by 64 v_mov_b64 (on top of the hand-over gap trim)
# speedup vs baseline: 1.0068x; 1.0041x over previous
.LBB0_102:
	s_ashr_i32 s19, s18, 31
	s_lshl_b64 s[20:21], s[18:19], 20
	s_add_u32 s20, s10, s20
	s_addc_u32 s21, s11, s21
	s_and_b64 s[22:23], s[0:1], exec
	s_cselect_b32 s19, s21, s25
	s_cselect_b32 s47, s20, s24
	s_ashr_i32 s17, s16, 31
	s_lshl_b64 s[22:23], s[16:17], 20
	s_add_u32 s22, s31, s22
	s_addc_u32 s23, s34, s23
	s_and_b64 s[28:29], s[0:1], exec
	s_cselect_b32 s17, s23, s27
	s_cselect_b32 s48, s22, s26
	s_add_u32 s24, s24, 0x80080
	s_addc_u32 s25, s25, 0
	s_add_u32 s49, s26, 0x100
	s_addc_u32 s64, s27, 0
	s_mov_b32 s65, -2
	v_mov_b64_e32 v[0:1], 0
	v_mov_b64_e32 v[2:3], 0
	v_mov_b64_e32 v[4:5], 0
	v_mov_b64_e32 v[6:7], 0
	v_mov_b64_e32 v[8:9], 0
	v_mov_b64_e32 v[10:11], 0
	v_mov_b64_e32 v[12:13], 0
	v_mov_b64_e32 v[14:15], 0
	v_mov_b64_e32 v[16:17], 0
	v_mov_b64_e32 v[18:19], 0
	v_mov_b64_e32 v[20:21], 0
	v_mov_b64_e32 v[22:23], 0
	v_mov_b64_e32 v[24:25], 0
	v_mov_b64_e32 v[26:27], 0
	v_mov_b64_e32 v[28:29], 0
	v_mov_b64_e32 v[30:31], 0
	v_mov_b64_e32 v[32:33], 0
	v_mov_b64_e32 v[34:35], 0
	v_mov_b64_e32 v[36:37], 0
	v_mov_b64_e32 v[38:39], 0
	v_mov_b64_e32 v[40:41], 0
	v_mov_b64_e32 v[42:43], 0
	v_mov_b64_e32 v[44:45], 0
	v_mov_b64_e32 v[46:47], 0
	v_mov_b64_e32 v[48:49], 0
	v_mov_b64_e32 v[50:51], 0
	v_mov_b64_e32 v[52:53], 0
	v_mov_b64_e32 v[54:55], 0
	v_mov_b64_e32 v[56:57], 0
	v_mov_b64_e32 v[58:59], 0
	v_mov_b64_e32 v[60:61], 0
	v_mov_b64_e32 v[62:63], 0
	v_mov_b64_e32 v[64:65], 0
	v_mov_b64_e32 v[66:67], 0
	v_mov_b64_e32 v[68:69], 0
	v_mov_b64_e32 v[70:71], 0
	v_mov_b64_e32 v[72:73], 0
	v_mov_b64_e32 v[74:75], 0
	v_mov_b64_e32 v[76:77], 0
	v_mov_b64_e32 v[78:79], 0
	v_mov_b64_e32 v[80:81], 0
	v_mov_b64_e32 v[82:83], 0
	v_mov_b64_e32 v[84:85], 0
	v_mov_b64_e32 v[86:87], 0
	v_mov_b64_e32 v[88:89], 0
	v_mov_b64_e32 v[90:91], 0
	v_mov_b64_e32 v[92:93], 0
	v_mov_b64_e32 v[94:95], 0
	v_mov_b64_e32 v[96:97], 0
	v_mov_b64_e32 v[98:99], 0
	v_mov_b64_e32 v[100:101], 0
	v_mov_b64_e32 v[102:103], 0
	v_mov_b64_e32 v[104:105], 0
	v_mov_b64_e32 v[106:107], 0
	v_mov_b64_e32 v[108:109], 0
	v_mov_b64_e32 v[110:111], 0
	v_mov_b64_e32 v[112:113], 0
	v_mov_b64_e32 v[114:115], 0
	v_mov_b64_e32 v[116:117], 0
	v_mov_b64_e32 v[118:119], 0
	v_mov_b64_e32 v[120:121], 0
	v_mov_b64_e32 v[122:123], 0
	v_mov_b64_e32 v[124:125], 0
	v_mov_b64_e32 v[126:127], 0

.LBB0_126:
	s_ashr_i32 s17, s16, 31
	s_lshl_b64 s[18:19], s[16:17], 20
	s_add_u32 s18, s6, s18
	s_addc_u32 s19, s7, s19
	s_and_b64 s[20:21], s[0:1], exec
	s_cselect_b32 s17, s19, s23
	s_cselect_b32 s46, s18, s22
	s_ashr_i32 s15, s14, 31
	s_lshl_b64 s[20:21], s[14:15], 20
	s_add_u32 s20, s30, s20
	s_addc_u32 s21, s31, s21
	s_and_b64 s[26:27], s[0:1], exec
	s_cselect_b32 s15, s21, s25
	s_cselect_b32 s47, s20, s24
	s_add_u32 s22, s22, 0x80080
	s_addc_u32 s23, s23, 0
	s_add_u32 s48, s24, 0x100
	s_addc_u32 s49, s25, 0
	s_mov_b32 s64, -2
	v_mov_b64_e32 v[0:1], 0
	v_mov_b64_e32 v[2:3], 0
	v_mov_b64_e32 v[4:5], 0
	v_mov_b64_e32 v[6:7], 0
	v_mov_b64_e32 v[8:9], 0
	v_mov_b64_e32 v[10:11], 0
	v_mov_b64_e32 v[12:13], 0
	v_mov_b64_e32 v[14:15], 0
	v_mov_b64_e32 v[16:17], 0
	v_mov_b64_e32 v[18:19], 0
	v_mov_b64_e32 v[20:21], 0
	v_mov_b64_e32 v[22:23], 0
	v_mov_b64_e32 v[24:25], 0
	v_mov_b64_e32 v[26:27], 0
	v_mov_b64_e32 v[28:29], 0
	v_mov_b64_e32 v[30:31], 0
	v_mov_b64_e32 v[32:33], 0
	v_mov_b64_e32 v[34:35], 0
	v_mov_b64_e32 v[36:37], 0
	v_mov_b64_e32 v[38:39], 0
	v_mov_b64_e32 v[40:41], 0
	v_mov_b64_e32 v[42:43], 0
	v_mov_b64_e32 v[44:45], 0
	v_mov_b64_e32 v[46:47], 0
	v_mov_b64_e32 v[48:49], 0
	v_mov_b64_e32 v[50:51], 0
	v_mov_b64_e32 v[52:53], 0
	v_mov_b64_e32 v[54:55], 0
	v_mov_b64_e32 v[56:57], 0
	v_mov_b64_e32 v[58:59], 0
	v_mov_b64_e32 v[60:61], 0
	v_mov_b64_e32 v[62:63], 0
	v_mov_b64_e32 v[64:65], 0
	v_mov_b64_e32 v[66:67], 0
	v_mov_b64_e32 v[68:69], 0
	v_mov_b64_e32 v[70:71], 0
	v_mov_b64_e32 v[72:73], 0
	v_mov_b64_e32 v[74:75], 0
	v_mov_b64_e32 v[76:77], 0
	v_mov_b64_e32 v[78:79], 0
	v_mov_b64_e32 v[80:81], 0
	v_mov_b64_e32 v[82:83], 0
	v_mov_b64_e32 v[84:85], 0
	v_mov_b64_e32 v[86:87], 0
	v_mov_b64_e32 v[88:89], 0
	v_mov_b64_e32 v[90:91], 0
	v_mov_b64_e32 v[92:93], 0
	v_mov_b64_e32 v[94:95], 0
	v_mov_b64_e32 v[96:97], 0
	v_mov_b64_e32 v[98:99], 0
	v_mov_b64_e32 v[100:101], 0
	v_mov_b64_e32 v[102:103], 0
	v_mov_b64_e32 v[104:105], 0
	v_mov_b64_e32 v[106:107], 0
	v_mov_b64_e32 v[108:109], 0
	v_mov_b64_e32 v[110:111], 0
	v_mov_b64_e32 v[112:113], 0
	v_mov_b64_e32 v[114:115], 0
	v_mov_b64_e32 v[116:117], 0
	v_mov_b64_e32 v[118:119], 0
	v_mov_b64_e32 v[120:121], 0
	v_mov_b64_e32 v[122:123], 0
	v_mov_b64_e32 v[124:125], 0
	v_mov_b64_e32 v[126:127], 0

.LBB0_142:
	s_ashr_i32 s15, s14, 31
	s_lshl_b64 s[16:17], s[14:15], 20
	s_add_u32 s16, s72, s16
	s_addc_u32 s17, s73, s17
	s_and_b64 s[18:19], s[0:1], exec
	s_cselect_b32 s15, s17, s23
	s_cselect_b32 s46, s16, s22
	s_ashr_i32 s13, s12, 31
	s_lshl_b64 s[18:19], s[12:13], 20
	s_add_u32 s18, s92, s18
	s_addc_u32 s19, s93, s19
	s_and_b64 s[26:27], s[0:1], exec
	s_cselect_b32 s13, s19, s25
	s_cselect_b32 s47, s18, s24
	s_add_u32 s22, s22, 0x80080
	s_addc_u32 s23, s23, 0
	s_add_u32 s48, s24, 0x100
	s_addc_u32 s49, s25, 0
	s_mov_b32 s64, -2
	v_mov_b64_e32 v[0:1], 0
	v_mov_b64_e32 v[2:3], 0
	v_mov_b64_e32 v[4:5], 0
	v_mov_b64_e32 v[6:7], 0
	v_mov_b64_e32 v[8:9], 0
	v_mov_b64_e32 v[10:11], 0
	v_mov_b64_e32 v[12:13], 0
	v_mov_b64_e32 v[14:15], 0
	v_mov_b64_e32 v[16:17], 0
	v_mov_b64_e32 v[18:19], 0
	v_mov_b64_e32 v[20:21], 0
	v_mov_b64_e32 v[22:23], 0
	v_mov_b64_e32 v[24:25], 0
	v_mov_b64_e32 v[26:27], 0
	v_mov_b64_e32 v[28:29], 0
	v_mov_b64_e32 v[30:31], 0
	v_mov_b64_e32 v[32:33], 0
	v_mov_b64_e32 v[34:35], 0
	v_mov_b64_e32 v[36:37], 0
	v_mov_b64_e32 v[38:39], 0
	v_mov_b64_e32 v[40:41], 0
	v_mov_b64_e32 v[42:43], 0
	v_mov_b64_e32 v[44:45], 0
	v_mov_b64_e32 v[46:47], 0
	v_mov_b64_e32 v[48:49], 0
	v_mov_b64_e32 v[50:51], 0
	v_mov_b64_e32 v[52:53], 0
	v_mov_b64_e32 v[54:55], 0
	v_mov_b64_e32 v[56:57], 0
	v_mov_b64_e32 v[58:59], 0
	v_mov_b64_e32 v[60:61], 0
	v_mov_b64_e32 v[62:63], 0
	v_mov_b64_e32 v[64:65], 0
	v_mov_b64_e32 v[66:67], 0
	v_mov_b64_e32 v[68:69], 0
	v_mov_b64_e32 v[70:71], 0
	v_mov_b64_e32 v[72:73], 0
	v_mov_b64_e32 v[74:75], 0
	v_mov_b64_e32 v[76:77], 0
	v_mov_b64_e32 v[78:79], 0
	v_mov_b64_e32 v[80:81], 0
	v_mov_b64_e32 v[82:83], 0
	v_mov_b64_e32 v[84:85], 0
	v_mov_b64_e32 v[86:87], 0
	v_mov_b64_e32 v[88:89], 0
	v_mov_b64_e32 v[90:91], 0
	v_mov_b64_e32 v[92:93], 0
	v_mov_b64_e32 v[94:95], 0
	v_mov_b64_e32 v[96:97], 0
	v_mov_b64_e32 v[98:99], 0
	v_mov_b64_e32 v[100:101], 0
	v_mov_b64_e32 v[102:103], 0
	v_mov_b64_e32 v[104:105], 0
	v_mov_b64_e32 v[106:107], 0
	v_mov_b64_e32 v[108:109], 0
	v_mov_b64_e32 v[110:111], 0
	v_mov_b64_e32 v[112:113], 0
	v_mov_b64_e32 v[114:115], 0
	v_mov_b64_e32 v[116:117], 0
	v_mov_b64_e32 v[118:119], 0
	v_mov_b64_e32 v[120:121], 0
	v_mov_b64_e32 v[122:123], 0
	v_mov_b64_e32 v[124:125], 0
	v_mov_b64_e32 v[126:127], 0

.LBB0_224:
	s_add_u32 s47, s24, 0x100
	s_addc_u32 s48, s25, 0
	s_mov_b32 s49, -2
	s_waitcnt lgkmcnt(0)
	v_mov_b64_e32 v[0:1], 0
	v_mov_b64_e32 v[2:3], 0
	v_mov_b64_e32 v[4:5], 0
	v_mov_b64_e32 v[6:7], 0
	v_mov_b64_e32 v[8:9], 0
	v_mov_b64_e32 v[10:11], 0
	v_mov_b64_e32 v[12:13], 0
	v_mov_b64_e32 v[14:15], 0
	v_mov_b64_e32 v[16:17], 0
	v_mov_b64_e32 v[18:19], 0
	v_mov_b64_e32 v[20:21], 0
	v_mov_b64_e32 v[22:23], 0
	v_mov_b64_e32 v[24:25], 0
	v_mov_b64_e32 v[26:27], 0
	v_mov_b64_e32 v[28:29], 0
	v_mov_b64_e32 v[30:31], 0
	v_mov_b64_e32 v[32:33], 0
	v_mov_b64_e32 v[34:35], 0
	v_mov_b64_e32 v[36:37], 0
	v_mov_b64_e32 v[38:39], 0
	v_mov_b64_e32 v[40:41], 0
	v_mov_b64_e32 v[42:43], 0
	v_mov_b64_e32 v[44:45], 0
	v_mov_b64_e32 v[46:47], 0
	v_mov_b64_e32 v[48:49], 0
	v_mov_b64_e32 v[50:51], 0
	v_mov_b64_e32 v[52:53], 0
	v_mov_b64_e32 v[54:55], 0
	v_mov_b64_e32 v[56:57], 0
	v_mov_b64_e32 v[58:59], 0
	v_mov_b64_e32 v[60:61], 0
	v_mov_b64_e32 v[62:63], 0
	v_mov_b64_e32 v[64:65], 0
	v_mov_b64_e32 v[66:67], 0
	v_mov_b64_e32 v[68:69], 0
	v_mov_b64_e32 v[70:71], 0
	v_mov_b64_e32 v[72:73], 0
	v_mov_b64_e32 v[74:75], 0
	v_mov_b64_e32 v[76:77], 0
	v_mov_b64_e32 v[78:79], 0
	v_mov_b64_e32 v[80:81], 0
	v_mov_b64_e32 v[82:83], 0
	v_mov_b64_e32 v[84:85], 0
	v_mov_b64_e32 v[86:87], 0
	v_mov_b64_e32 v[88:89], 0
	v_mov_b64_e32 v[90:91], 0
	v_mov_b64_e32 v[92:93], 0
	v_mov_b64_e32 v[94:95], 0
	v_mov_b64_e32 v[96:97], 0
	v_mov_b64_e32 v[98:99], 0
	v_mov_b64_e32 v[100:101], 0
	v_mov_b64_e32 v[102:103], 0
	v_mov_b64_e32 v[104:105], 0
	v_mov_b64_e32 v[106:107], 0
	v_mov_b64_e32 v[108:109], 0
	v_mov_b64_e32 v[110:111], 0
	v_mov_b64_e32 v[112:113], 0
	v_mov_b64_e32 v[114:115], 0
	v_mov_b64_e32 v[116:117], 0
	v_mov_b64_e32 v[118:119], 0
	v_mov_b64_e32 v[120:121], 0
	v_mov_b64_e32 v[122:123], 0
	v_mov_b64_e32 v[124:125], 0
	v_mov_b64_e32 v[126:127], 0

.LBB0_310:
	s_ashr_i32 s15, s14, 31
	s_lshl_b64 s[16:17], s[14:15], 20
	s_add_u32 s16, s72, s16
	s_addc_u32 s17, s73, s17
	s_and_b64 s[18:19], s[4:5], exec
	s_cselect_b32 s15, s17, s23
	s_cselect_b32 s46, s16, s22
	s_ashr_i32 s13, s12, 31
	s_lshl_b64 s[18:19], s[12:13], 20
	s_add_u32 s18, s82, s18
	s_addc_u32 s19, s83, s19
	s_and_b64 s[26:27], s[4:5], exec
	s_cselect_b32 s13, s19, s25
	s_cselect_b32 s47, s18, s24
	s_add_u32 s22, s22, 0x80080
	s_addc_u32 s23, s23, 0
	s_add_u32 s48, s24, 0x100
	s_addc_u32 s49, s25, 0
	s_mov_b32 s64, -2
	v_mov_b64_e32 v[0:1], 0
	v_mov_b64_e32 v[2:3], 0
	v_mov_b64_e32 v[4:5], 0
	v_mov_b64_e32 v[6:7], 0
	v_mov_b64_e32 v[8:9], 0
	v_mov_b64_e32 v[10:11], 0
	v_mov_b64_e32 v[12:13], 0
	v_mov_b64_e32 v[14:15], 0
	v_mov_b64_e32 v[16:17], 0
	v_mov_b64_e32 v[18:19], 0
	v_mov_b64_e32 v[20:21], 0
	v_mov_b64_e32 v[22:23], 0
	v_mov_b64_e32 v[24:25], 0
	v_mov_b64_e32 v[26:27], 0
	v_mov_b64_e32 v[28:29], 0
	v_mov_b64_e32 v[30:31], 0
	v_mov_b64_e32 v[32:33], 0
	v_mov_b64_e32 v[34:35], 0
	v_mov_b64_e32 v[36:37], 0
	v_mov_b64_e32 v[38:39], 0
	v_mov_b64_e32 v[40:41], 0
	v_mov_b64_e32 v[42:43], 0
	v_mov_b64_e32 v[44:45], 0
	v_mov_b64_e32 v[46:47], 0
	v_mov_b64_e32 v[48:49], 0
	v_mov_b64_e32 v[50:51], 0
	v_mov_b64_e32 v[52:53], 0
	v_mov_b64_e32 v[54:55], 0
	v_mov_b64_e32 v[56:57], 0
	v_mov_b64_e32 v[58:59], 0
	v_mov_b64_e32 v[60:61], 0
	v_mov_b64_e32 v[62:63], 0
	v_mov_b64_e32 v[64:65], 0
	v_mov_b64_e32 v[66:67], 0
	v_mov_b64_e32 v[68:69], 0
	v_mov_b64_e32 v[70:71], 0
	v_mov_b64_e32 v[72:73], 0
	v_mov_b64_e32 v[74:75], 0
	v_mov_b64_e32 v[76:77], 0
	v_mov_b64_e32 v[78:79], 0
	v_mov_b64_e32 v[80:81], 0
	v_mov_b64_e32 v[82:83], 0
	v_mov_b64_e32 v[84:85], 0
	v_mov_b64_e32 v[86:87], 0
	v_mov_b64_e32 v[88:89], 0
	v_mov_b64_e32 v[90:91], 0
	v_mov_b64_e32 v[92:93], 0
	v_mov_b64_e32 v[94:95], 0
	v_mov_b64_e32 v[96:97], 0
	v_mov_b64_e32 v[98:99], 0
	v_mov_b64_e32 v[100:101], 0
	v_mov_b64_e32 v[102:103], 0
	v_mov_b64_e32 v[104:105], 0
	v_mov_b64_e32 v[106:107], 0
	v_mov_b64_e32 v[108:109], 0
	v_mov_b64_e32 v[110:111], 0
	v_mov_b64_e32 v[112:113], 0
	v_mov_b64_e32 v[114:115], 0
	v_mov_b64_e32 v[116:117], 0
	v_mov_b64_e32 v[118:119], 0
	v_mov_b64_e32 v[120:121], 0
	v_mov_b64_e32 v[122:123], 0
	v_mov_b64_e32 v[124:125], 0
	v_mov_b64_e32 v[126:127], 0

.LBB0_704:
	s_ashr_i32 s25, s24, 31
	s_lshl_b64 s[26:27], s[24:25], 20
	s_add_u32 s26, s60, s26
	s_addc_u32 s27, s61, s27
	s_and_b64 s[28:29], s[10:11], exec
	s_cselect_b32 s13, s27, s35
	s_cselect_b32 s25, s26, s34
	s_ashr_i32 s23, s22, 31
	s_lshl_b64 s[28:29], s[22:23], 20
	s_add_u32 s28, s96, s28
	s_addc_u32 s29, s97, s29
	s_and_b64 s[38:39], s[10:11], exec
	s_cselect_b32 s23, s29, s37
	s_cselect_b32 s31, s28, s36
	s_add_u32 s34, s34, 0x80080
	s_addc_u32 s35, s35, 0
	s_add_u32 s53, s36, 0x100
	s_addc_u32 s54, s37, 0
	s_mov_b32 s55, -2
	s_waitcnt lgkmcnt(0)
	v_mov_b64_e32 v[0:1], 0
	v_mov_b64_e32 v[2:3], 0
	v_mov_b64_e32 v[4:5], 0
	v_mov_b64_e32 v[6:7], 0
	v_mov_b64_e32 v[8:9], 0
	v_mov_b64_e32 v[10:11], 0
	v_mov_b64_e32 v[12:13], 0
	v_mov_b64_e32 v[14:15], 0
	v_mov_b64_e32 v[16:17], 0
	v_mov_b64_e32 v[18:19], 0
	v_mov_b64_e32 v[20:21], 0
	v_mov_b64_e32 v[22:23], 0
	v_mov_b64_e32 v[24:25], 0
	v_mov_b64_e32 v[26:27], 0
	v_mov_b64_e32 v[28:29], 0
	v_mov_b64_e32 v[30:31], 0
	v_mov_b64_e32 v[32:33], 0
	v_mov_b64_e32 v[34:35], 0
	v_mov_b64_e32 v[36:37], 0
	v_mov_b64_e32 v[38:39], 0
	v_mov_b64_e32 v[40:41], 0
	v_mov_b64_e32 v[42:43], 0
	v_mov_b64_e32 v[44:45], 0
	v_mov_b64_e32 v[46:47], 0
	v_mov_b64_e32 v[48:49], 0
	v_mov_b64_e32 v[50:51], 0
	v_mov_b64_e32 v[52:53], 0
	v_mov_b64_e32 v[54:55], 0
	v_mov_b64_e32 v[56:57], 0
	v_mov_b64_e32 v[58:59], 0
	v_mov_b64_e32 v[60:61], 0
	v_mov_b64_e32 v[62:63], 0
	v_mov_b64_e32 v[64:65], 0
	v_mov_b64_e32 v[66:67], 0
	v_mov_b64_e32 v[68:69], 0
	v_mov_b64_e32 v[70:71], 0
	v_mov_b64_e32 v[72:73], 0
	v_mov_b64_e32 v[74:75], 0
	v_mov_b64_e32 v[76:77], 0
	v_mov_b64_e32 v[78:79], 0
	v_mov_b64_e32 v[80:81], 0
	v_mov_b64_e32 v[82:83], 0
	v_mov_b64_e32 v[84:85], 0
	v_mov_b64_e32 v[86:87], 0
	v_mov_b64_e32 v[88:89], 0
	v_mov_b64_e32 v[90:91], 0
	v_mov_b64_e32 v[92:93], 0
	v_mov_b64_e32 v[94:95], 0
	v_mov_b64_e32 v[96:97], 0
	v_mov_b64_e32 v[98:99], 0
	v_mov_b64_e32 v[100:101], 0
	v_mov_b64_e32 v[102:103], 0
	v_mov_b64_e32 v[104:105], 0
	v_mov_b64_e32 v[106:107], 0
	v_mov_b64_e32 v[108:109], 0
	v_mov_b64_e32 v[110:111], 0
	v_mov_b64_e32 v[112:113], 0
	v_mov_b64_e32 v[114:115], 0
	v_mov_b64_e32 v[116:117], 0
	v_mov_b64_e32 v[118:119], 0
	v_mov_b64_e32 v[120:121], 0
	v_mov_b64_e32 v[122:123], 0
	v_mov_b64_e32 v[124:125], 0
	v_mov_b64_e32 v[126:127], 0

.LBB0_798:
	s_ashr_i32 s17, s16, 31
	s_lshl_b64 s[22:23], s[16:17], 20
	s_add_u32 s22, s72, s22
	s_addc_u32 s23, s73, s23
	s_and_b64 s[24:25], s[6:7], exec
	s_cselect_b32 s17, s23, s29
	s_cselect_b32 s48, s22, s28
	s_ashr_i32 s15, s14, 31
	s_lshl_b64 s[24:25], s[14:15], 20
	s_add_u32 s24, s78, s24
	s_addc_u32 s25, s79, s25
	s_and_b64 s[34:35], s[6:7], exec
	s_cselect_b32 s15, s25, s31
	s_cselect_b32 s49, s24, s30
	s_add_u32 s28, s28, 0x80080
	s_addc_u32 s29, s29, 0
	s_add_u32 s52, s30, 0x100
	s_addc_u32 s53, s31, 0
	s_mov_b32 s54, -2
	v_mov_b64_e32 v[0:1], 0
	v_mov_b64_e32 v[2:3], 0
	v_mov_b64_e32 v[4:5], 0
	v_mov_b64_e32 v[6:7], 0
	v_mov_b64_e32 v[8:9], 0
	v_mov_b64_e32 v[10:11], 0
	v_mov_b64_e32 v[12:13], 0
	v_mov_b64_e32 v[14:15], 0
	v_mov_b64_e32 v[16:17], 0
	v_mov_b64_e32 v[18:19], 0
	v_mov_b64_e32 v[20:21], 0
	v_mov_b64_e32 v[22:23], 0
	v_mov_b64_e32 v[24:25], 0
	v_mov_b64_e32 v[26:27], 0
	v_mov_b64_e32 v[28:29], 0
	v_mov_b64_e32 v[30:31], 0
	v_mov_b64_e32 v[32:33], 0
	v_mov_b64_e32 v[34:35], 0
	v_mov_b64_e32 v[36:37], 0
	v_mov_b64_e32 v[38:39], 0
	v_mov_b64_e32 v[40:41], 0
	v_mov_b64_e32 v[42:43], 0
	v_mov_b64_e32 v[44:45], 0
	v_mov_b64_e32 v[46:47], 0
	v_mov_b64_e32 v[48:49], 0
	v_mov_b64_e32 v[50:51], 0
	v_mov_b64_e32 v[52:53], 0
	v_mov_b64_e32 v[54:55], 0
	v_mov_b64_e32 v[56:57], 0
	v_mov_b64_e32 v[58:59], 0
	v_mov_b64_e32 v[60:61], 0
	v_mov_b64_e32 v[62:63], 0
	v_mov_b64_e32 v[64:65], 0
	v_mov_b64_e32 v[66:67], 0
	v_mov_b64_e32 v[68:69], 0
	v_mov_b64_e32 v[70:71], 0
	v_mov_b64_e32 v[72:73], 0
	v_mov_b64_e32 v[74:75], 0
	v_mov_b64_e32 v[76:77], 0
	v_mov_b64_e32 v[78:79], 0
	v_mov_b64_e32 v[80:81], 0
	v_mov_b64_e32 v[82:83], 0
	v_mov_b64_e32 v[84:85], 0
	v_mov_b64_e32 v[86:87], 0
	v_mov_b64_e32 v[88:89], 0
	v_mov_b64_e32 v[90:91], 0
	v_mov_b64_e32 v[92:93], 0
	v_mov_b64_e32 v[94:95], 0
	v_mov_b64_e32 v[96:97], 0
	v_mov_b64_e32 v[98:99], 0
	v_mov_b64_e32 v[100:101], 0
	v_mov_b64_e32 v[102:103], 0
	v_mov_b64_e32 v[104:105], 0
	v_mov_b64_e32 v[106:107], 0
	v_mov_b64_e32 v[108:109], 0
	v_mov_b64_e32 v[110:111], 0
	v_mov_b64_e32 v[112:113], 0
	v_mov_b64_e32 v[114:115], 0
	v_mov_b64_e32 v[116:117], 0
	v_mov_b64_e32 v[118:119], 0
	v_mov_b64_e32 v[120:121], 0
	v_mov_b64_e32 v[122:123], 0
	v_mov_b64_e32 v[124:125], 0
	v_mov_b64_e32 v[126:127], 0

.LBB0_933:
	s_ashr_i32 s29, s28, 31
	s_lshl_b64 s[30:31], s[28:29], 20
	s_add_u32 s30, s60, s30
	s_addc_u32 s31, s61, s31
	s_and_b64 s[34:35], s[10:11], exec
	s_cselect_b32 s13, s31, s39
	s_cselect_b32 s29, s30, s38
	s_ashr_i32 s27, s26, 31
	s_lshl_b64 s[34:35], s[26:27], 20
	v_readlane_b32 s18, v244, 61
	v_readlane_b32 s19, v244, 62
	s_add_u32 s34, s18, s34
	s_addc_u32 s35, s19, s35
	s_and_b64 s[42:43], s[10:11], exec
	s_cselect_b32 s27, s35, s41
	s_cselect_b32 s37, s34, s40
	s_add_u32 s38, s38, 0x80080
	s_addc_u32 s39, s39, 0
	s_add_u32 s57, s40, 0x100
	s_addc_u32 s58, s41, 0
	s_mov_b32 s59, -2
	s_waitcnt lgkmcnt(0)
	v_mov_b64_e32 v[0:1], 0
	v_mov_b64_e32 v[2:3], 0
	v_mov_b64_e32 v[4:5], 0
	v_mov_b64_e32 v[6:7], 0
	v_mov_b64_e32 v[8:9], 0
	v_mov_b64_e32 v[10:11], 0
	v_mov_b64_e32 v[12:13], 0
	v_mov_b64_e32 v[14:15], 0
	v_mov_b64_e32 v[16:17], 0
	v_mov_b64_e32 v[18:19], 0
	v_mov_b64_e32 v[20:21], 0
	v_mov_b64_e32 v[22:23], 0
	v_mov_b64_e32 v[24:25], 0
	v_mov_b64_e32 v[26:27], 0
	v_mov_b64_e32 v[28:29], 0
	v_mov_b64_e32 v[30:31], 0
	v_mov_b64_e32 v[32:33], 0
	v_mov_b64_e32 v[34:35], 0
	v_mov_b64_e32 v[36:37], 0
	v_mov_b64_e32 v[38:39], 0
	v_mov_b64_e32 v[40:41], 0
	v_mov_b64_e32 v[42:43], 0
	v_mov_b64_e32 v[44:45], 0
	v_mov_b64_e32 v[46:47], 0
	v_mov_b64_e32 v[48:49], 0
	v_mov_b64_e32 v[50:51], 0
	v_mov_b64_e32 v[52:53], 0
	v_mov_b64_e32 v[54:55], 0
	v_mov_b64_e32 v[56:57], 0
	v_mov_b64_e32 v[58:59], 0
	v_mov_b64_e32 v[60:61], 0
	v_mov_b64_e32 v[62:63], 0
	v_mov_b64_e32 v[64:65], 0
	v_mov_b64_e32 v[66:67], 0
	v_mov_b64_e32 v[68:69], 0
	v_mov_b64_e32 v[70:71], 0
	v_mov_b64_e32 v[72:73], 0
	v_mov_b64_e32 v[74:75], 0
	v_mov_b64_e32 v[76:77], 0
	v_mov_b64_e32 v[78:79], 0
	v_mov_b64_e32 v[80:81], 0
	v_mov_b64_e32 v[82:83], 0
	v_mov_b64_e32 v[84:85], 0
	v_mov_b64_e32 v[86:87], 0
	v_mov_b64_e32 v[88:89], 0
	v_mov_b64_e32 v[90:91], 0
	v_mov_b64_e32 v[92:93], 0
	v_mov_b64_e32 v[94:95], 0
	v_mov_b64_e32 v[96:97], 0
	v_mov_b64_e32 v[98:99], 0
	v_mov_b64_e32 v[100:101], 0
	v_mov_b64_e32 v[102:103], 0
	v_mov_b64_e32 v[104:105], 0
	v_mov_b64_e32 v[106:107], 0
	v_mov_b64_e32 v[108:109], 0
	v_mov_b64_e32 v[110:111], 0
	v_mov_b64_e32 v[112:113], 0
	v_mov_b64_e32 v[114:115], 0
	v_mov_b64_e32 v[116:117], 0
	v_mov_b64_e32 v[118:119], 0
	v_mov_b64_e32 v[120:121], 0
	v_mov_b64_e32 v[122:123], 0
	v_mov_b64_e32 v[124:125], 0
	v_mov_b64_e32 v[126:127], 0

.LBB0_1019:
	s_ashr_i32 s27, s26, 31
	s_lshl_b64 s[28:29], s[26:27], 20
	s_add_u32 s28, s72, s28
	s_addc_u32 s29, s73, s29
	s_and_b64 s[30:31], s[8:9], exec
	s_cselect_b32 s27, s29, s37
	s_cselect_b32 s58, s28, s36
	s_ashr_i32 s17, s16, 31
	s_lshl_b64 s[30:31], s[16:17], 20
	s_add_u32 s30, s24, s30
	s_addc_u32 s31, s25, s31
	s_and_b64 s[40:41], s[8:9], exec
	s_cselect_b32 s17, s31, s39
	s_cselect_b32 s59, s30, s38
	s_add_u32 s36, s36, 0x80080
	s_addc_u32 s37, s37, 0
	s_add_u32 s62, s38, 0x100
	s_addc_u32 s63, s39, 0
	s_mov_b32 s64, -2
	v_mov_b64_e32 v[0:1], 0
	v_mov_b64_e32 v[2:3], 0
	v_mov_b64_e32 v[4:5], 0
	v_mov_b64_e32 v[6:7], 0
	v_mov_b64_e32 v[8:9], 0
	v_mov_b64_e32 v[10:11], 0
	v_mov_b64_e32 v[12:13], 0
	v_mov_b64_e32 v[14:15], 0
	v_mov_b64_e32 v[16:17], 0
	v_mov_b64_e32 v[18:19], 0
	v_mov_b64_e32 v[20:21], 0
	v_mov_b64_e32 v[22:23], 0
	v_mov_b64_e32 v[24:25], 0
	v_mov_b64_e32 v[26:27], 0
	v_mov_b64_e32 v[28:29], 0
	v_mov_b64_e32 v[30:31], 0
	v_mov_b64_e32 v[32:33], 0
	v_mov_b64_e32 v[34:35], 0
	v_mov_b64_e32 v[36:37], 0
	v_mov_b64_e32 v[38:39], 0
	v_mov_b64_e32 v[40:41], 0
	v_mov_b64_e32 v[42:43], 0
	v_mov_b64_e32 v[44:45], 0
	v_mov_b64_e32 v[46:47], 0
	v_mov_b64_e32 v[48:49], 0
	v_mov_b64_e32 v[50:51], 0
	v_mov_b64_e32 v[52:53], 0
	v_mov_b64_e32 v[54:55], 0
	v_mov_b64_e32 v[56:57], 0
	v_mov_b64_e32 v[58:59], 0
	v_mov_b64_e32 v[60:61], 0
	v_mov_b64_e32 v[62:63], 0
	v_mov_b64_e32 v[64:65], 0
	v_mov_b64_e32 v[66:67], 0
	v_mov_b64_e32 v[68:69], 0
	v_mov_b64_e32 v[70:71], 0
	v_mov_b64_e32 v[72:73], 0
	v_mov_b64_e32 v[74:75], 0
	v_mov_b64_e32 v[76:77], 0
	v_mov_b64_e32 v[78:79], 0
	v_mov_b64_e32 v[80:81], 0
	v_mov_b64_e32 v[82:83], 0
	v_mov_b64_e32 v[84:85], 0
	v_mov_b64_e32 v[86:87], 0
	v_mov_b64_e32 v[88:89], 0
	v_mov_b64_e32 v[90:91], 0
	v_mov_b64_e32 v[92:93], 0
	v_mov_b64_e32 v[94:95], 0
	v_mov_b64_e32 v[96:97], 0
	v_mov_b64_e32 v[98:99], 0
	v_mov_b64_e32 v[100:101], 0
	v_mov_b64_e32 v[102:103], 0
	v_mov_b64_e32 v[104:105], 0
	v_mov_b64_e32 v[106:107], 0
	v_mov_b64_e32 v[108:109], 0
	v_mov_b64_e32 v[110:111], 0
	v_mov_b64_e32 v[112:113], 0
	v_mov_b64_e32 v[114:115], 0
	v_mov_b64_e32 v[116:117], 0
	v_mov_b64_e32 v[118:119], 0
	v_mov_b64_e32 v[120:121], 0
	v_mov_b64_e32 v[122:123], 0
	v_mov_b64_e32 v[124:125], 0
	v_mov_b64_e32 v[126:127], 0

.LBB0_1101:
	s_add_u32 s63, s40, 0x100
	s_addc_u32 s64, s41, 0
	s_mov_b32 s65, -2
	s_waitcnt lgkmcnt(0)
	v_mov_b64_e32 v[0:1], 0
	v_mov_b64_e32 v[2:3], 0
	v_mov_b64_e32 v[4:5], 0
	v_mov_b64_e32 v[6:7], 0
	v_mov_b64_e32 v[8:9], 0
	v_mov_b64_e32 v[10:11], 0
	v_mov_b64_e32 v[12:13], 0
	v_mov_b64_e32 v[14:15], 0
	v_mov_b64_e32 v[16:17], 0
	v_mov_b64_e32 v[18:19], 0
	v_mov_b64_e32 v[20:21], 0
	v_mov_b64_e32 v[22:23], 0
	v_mov_b64_e32 v[24:25], 0
	v_mov_b64_e32 v[26:27], 0
	v_mov_b64_e32 v[28:29], 0
	v_mov_b64_e32 v[30:31], 0
	v_mov_b64_e32 v[32:33], 0
	v_mov_b64_e32 v[34:35], 0
	v_mov_b64_e32 v[36:37], 0
	v_mov_b64_e32 v[38:39], 0
	v_mov_b64_e32 v[40:41], 0
	v_mov_b64_e32 v[42:43], 0
	v_mov_b64_e32 v[44:45], 0
	v_mov_b64_e32 v[46:47], 0
	v_mov_b64_e32 v[48:49], 0
	v_mov_b64_e32 v[50:51], 0
	v_mov_b64_e32 v[52:53], 0
	v_mov_b64_e32 v[54:55], 0
	v_mov_b64_e32 v[56:57], 0
	v_mov_b64_e32 v[58:59], 0
	v_mov_b64_e32 v[60:61], 0
	v_mov_b64_e32 v[62:63], 0
	v_mov_b64_e32 v[64:65], 0
	v_mov_b64_e32 v[66:67], 0
	v_mov_b64_e32 v[68:69], 0
	v_mov_b64_e32 v[70:71], 0
	v_mov_b64_e32 v[72:73], 0
	v_mov_b64_e32 v[74:75], 0
	v_mov_b64_e32 v[76:77], 0
	v_mov_b64_e32 v[78:79], 0
	v_mov_b64_e32 v[80:81], 0
	v_mov_b64_e32 v[82:83], 0
	v_mov_b64_e32 v[84:85], 0
	v_mov_b64_e32 v[86:87], 0
	v_mov_b64_e32 v[88:89], 0
	v_mov_b64_e32 v[90:91], 0
	v_mov_b64_e32 v[92:93], 0
	v_mov_b64_e32 v[94:95], 0
	v_mov_b64_e32 v[96:97], 0
	v_mov_b64_e32 v[98:99], 0
	v_mov_b64_e32 v[100:101], 0
	v_mov_b64_e32 v[102:103], 0
	v_mov_b64_e32 v[104:105], 0
	v_mov_b64_e32 v[106:107], 0
	v_mov_b64_e32 v[108:109], 0
	v_mov_b64_e32 v[110:111], 0
	v_mov_b64_e32 v[112:113], 0
	v_mov_b64_e32 v[114:115], 0
	v_mov_b64_e32 v[116:117], 0
	v_mov_b64_e32 v[118:119], 0
	v_mov_b64_e32 v[120:121], 0
	v_mov_b64_e32 v[122:123], 0
	v_mov_b64_e32 v[124:125], 0
	v_mov_b64_e32 v[126:127], 0

.LBB0_1312:
	s_ashr_i32 s37, s36, 31
	s_lshl_b64 s[38:39], s[36:37], 20
	s_add_u32 s38, s72, s38
	s_addc_u32 s39, s73, s39
	s_and_b64 s[40:41], s[12:13], exec
	s_cselect_b32 s37, s39, s43
	s_cselect_b32 s66, s38, s42
	s_ashr_i32 s35, s34, 31
	s_lshl_b64 s[40:41], s[34:35], 20
	s_add_u32 s40, s92, s40
	s_addc_u32 s41, s93, s41
	s_and_b64 s[46:47], s[12:13], exec
	s_cselect_b32 s35, s41, s45
	s_cselect_b32 s67, s40, s44
	s_add_u32 s42, s42, 0x80080
	s_addc_u32 s43, s43, 0
	s_add_u32 s69, s44, 0x100
	s_addc_u32 s71, s45, 0
	s_mov_b32 s77, -2
	v_mov_b64_e32 v[0:1], 0
	v_mov_b64_e32 v[2:3], 0
	v_mov_b64_e32 v[4:5], 0
	v_mov_b64_e32 v[6:7], 0
	v_mov_b64_e32 v[8:9], 0
	v_mov_b64_e32 v[10:11], 0
	v_mov_b64_e32 v[12:13], 0
	v_mov_b64_e32 v[14:15], 0
	v_mov_b64_e32 v[16:17], 0
	v_mov_b64_e32 v[18:19], 0
	v_mov_b64_e32 v[20:21], 0
	v_mov_b64_e32 v[22:23], 0
	v_mov_b64_e32 v[24:25], 0
	v_mov_b64_e32 v[26:27], 0
	v_mov_b64_e32 v[28:29], 0
	v_mov_b64_e32 v[30:31], 0
	v_mov_b64_e32 v[32:33], 0
	v_mov_b64_e32 v[34:35], 0
	v_mov_b64_e32 v[36:37], 0
	v_mov_b64_e32 v[38:39], 0
	v_mov_b64_e32 v[40:41], 0
	v_mov_b64_e32 v[42:43], 0
	v_mov_b64_e32 v[44:45], 0
	v_mov_b64_e32 v[46:47], 0
	v_mov_b64_e32 v[48:49], 0
	v_mov_b64_e32 v[50:51], 0
	v_mov_b64_e32 v[52:53], 0
	v_mov_b64_e32 v[54:55], 0
	v_mov_b64_e32 v[56:57], 0
	v_mov_b64_e32 v[58:59], 0
	v_mov_b64_e32 v[60:61], 0
	v_mov_b64_e32 v[62:63], 0
	v_mov_b64_e32 v[64:65], 0
	v_mov_b64_e32 v[66:67], 0
	v_mov_b64_e32 v[68:69], 0
	v_mov_b64_e32 v[70:71], 0
	v_mov_b64_e32 v[72:73], 0
	v_mov_b64_e32 v[74:75], 0
	v_mov_b64_e32 v[76:77], 0
	v_mov_b64_e32 v[78:79], 0
	v_mov_b64_e32 v[80:81], 0
	v_mov_b64_e32 v[82:83], 0
	v_mov_b64_e32 v[84:85], 0
	v_mov_b64_e32 v[86:87], 0
	v_mov_b64_e32 v[88:89], 0
	v_mov_b64_e32 v[90:91], 0
	v_mov_b64_e32 v[92:93], 0
	v_mov_b64_e32 v[94:95], 0
	v_mov_b64_e32 v[96:97], 0
	v_mov_b64_e32 v[98:99], 0
	v_mov_b64_e32 v[100:101], 0
	v_mov_b64_e32 v[102:103], 0
	v_mov_b64_e32 v[104:105], 0
	v_mov_b64_e32 v[106:107], 0
	v_mov_b64_e32 v[108:109], 0
	v_mov_b64_e32 v[110:111], 0
	v_mov_b64_e32 v[112:113], 0
	v_mov_b64_e32 v[114:115], 0
	v_mov_b64_e32 v[116:117], 0
	v_mov_b64_e32 v[118:119], 0
	v_mov_b64_e32 v[120:121], 0
	v_mov_b64_e32 v[122:123], 0
	v_mov_b64_e32 v[124:125], 0
	v_mov_b64_e32 v[126:127], 0

.LBB0_1394:
	s_add_u32 s67, s44, 0x100
	s_addc_u32 s69, s45, 0
	s_mov_b32 s71, -2
	s_waitcnt lgkmcnt(0)
	v_mov_b64_e32 v[0:1], 0
	v_mov_b64_e32 v[2:3], 0
	v_mov_b64_e32 v[4:5], 0
	v_mov_b64_e32 v[6:7], 0
	v_mov_b64_e32 v[8:9], 0
	v_mov_b64_e32 v[10:11], 0
	v_mov_b64_e32 v[12:13], 0
	v_mov_b64_e32 v[14:15], 0
	v_mov_b64_e32 v[16:17], 0
	v_mov_b64_e32 v[18:19], 0
	v_mov_b64_e32 v[20:21], 0
	v_mov_b64_e32 v[22:23], 0
	v_mov_b64_e32 v[24:25], 0
	v_mov_b64_e32 v[26:27], 0
	v_mov_b64_e32 v[28:29], 0
	v_mov_b64_e32 v[30:31], 0
	v_mov_b64_e32 v[32:33], 0
	v_mov_b64_e32 v[34:35], 0
	v_mov_b64_e32 v[36:37], 0
	v_mov_b64_e32 v[38:39], 0
	v_mov_b64_e32 v[40:41], 0
	v_mov_b64_e32 v[42:43], 0
	v_mov_b64_e32 v[44:45], 0
	v_mov_b64_e32 v[46:47], 0
	v_mov_b64_e32 v[48:49], 0
	v_mov_b64_e32 v[50:51], 0
	v_mov_b64_e32 v[52:53], 0
	v_mov_b64_e32 v[54:55], 0
	v_mov_b64_e32 v[56:57], 0
	v_mov_b64_e32 v[58:59], 0
	v_mov_b64_e32 v[60:61], 0
	v_mov_b64_e32 v[62:63], 0
	v_mov_b64_e32 v[64:65], 0
	v_mov_b64_e32 v[66:67], 0
	v_mov_b64_e32 v[68:69], 0
	v_mov_b64_e32 v[70:71], 0
	v_mov_b64_e32 v[72:73], 0
	v_mov_b64_e32 v[74:75], 0
	v_mov_b64_e32 v[76:77], 0
	v_mov_b64_e32 v[78:79], 0
	v_mov_b64_e32 v[80:81], 0
	v_mov_b64_e32 v[82:83], 0
	v_mov_b64_e32 v[84:85], 0
	v_mov_b64_e32 v[86:87], 0
	v_mov_b64_e32 v[88:89], 0
	v_mov_b64_e32 v[90:91], 0
	v_mov_b64_e32 v[92:93], 0
	v_mov_b64_e32 v[94:95], 0
	v_mov_b64_e32 v[96:97], 0
	v_mov_b64_e32 v[98:99], 0
	v_mov_b64_e32 v[100:101], 0
	v_mov_b64_e32 v[102:103], 0
	v_mov_b64_e32 v[104:105], 0
	v_mov_b64_e32 v[106:107], 0
	v_mov_b64_e32 v[108:109], 0
	v_mov_b64_e32 v[110:111], 0
	v_mov_b64_e32 v[112:113], 0
	v_mov_b64_e32 v[114:115], 0
	v_mov_b64_e32 v[116:117], 0
	v_mov_b64_e32 v[118:119], 0
	v_mov_b64_e32 v[120:121], 0
	v_mov_b64_e32 v[122:123], 0
	v_mov_b64_e32 v[124:125], 0
	v_mov_b64_e32 v[126:127], 0

.LBB0_1480:
	s_ashr_i32 s37, s36, 31
	s_lshl_b64 s[38:39], s[36:37], 20
	s_add_u32 s38, s72, s38
	s_addc_u32 s39, s73, s39
	s_and_b64 s[40:41], s[12:13], exec
	s_cselect_b32 s37, s39, s43
	s_cselect_b32 s66, s38, s42
	s_ashr_i32 s35, s34, 31
	s_lshl_b64 s[40:41], s[34:35], 20
	s_add_u32 s40, s82, s40
	s_addc_u32 s41, s83, s41
	s_and_b64 s[46:47], s[12:13], exec
	s_cselect_b32 s35, s41, s45
	s_cselect_b32 s67, s40, s44
	s_add_u32 s42, s42, 0x80080
	s_addc_u32 s43, s43, 0
	s_add_u32 s69, s44, 0x100
	s_addc_u32 s71, s45, 0
	s_mov_b32 s77, -2
	v_mov_b64_e32 v[0:1], 0
	v_mov_b64_e32 v[2:3], 0
	v_mov_b64_e32 v[4:5], 0
	v_mov_b64_e32 v[6:7], 0
	v_mov_b64_e32 v[8:9], 0
	v_mov_b64_e32 v[10:11], 0
	v_mov_b64_e32 v[12:13], 0
	v_mov_b64_e32 v[14:15], 0
	v_mov_b64_e32 v[16:17], 0
	v_mov_b64_e32 v[18:19], 0
	v_mov_b64_e32 v[20:21], 0
	v_mov_b64_e32 v[22:23], 0
	v_mov_b64_e32 v[24:25], 0
	v_mov_b64_e32 v[26:27], 0
	v_mov_b64_e32 v[28:29], 0
	v_mov_b64_e32 v[30:31], 0
	v_mov_b64_e32 v[32:33], 0
	v_mov_b64_e32 v[34:35], 0
	v_mov_b64_e32 v[36:37], 0
	v_mov_b64_e32 v[38:39], 0
	v_mov_b64_e32 v[40:41], 0
	v_mov_b64_e32 v[42:43], 0
	v_mov_b64_e32 v[44:45], 0
	v_mov_b64_e32 v[46:47], 0
	v_mov_b64_e32 v[48:49], 0
	v_mov_b64_e32 v[50:51], 0
	v_mov_b64_e32 v[52:53], 0
	v_mov_b64_e32 v[54:55], 0
	v_mov_b64_e32 v[56:57], 0
	v_mov_b64_e32 v[58:59], 0
	v_mov_b64_e32 v[60:61], 0
	v_mov_b64_e32 v[62:63], 0
	v_mov_b64_e32 v[64:65], 0
	v_mov_b64_e32 v[66:67], 0
	v_mov_b64_e32 v[68:69], 0
	v_mov_b64_e32 v[70:71], 0
	v_mov_b64_e32 v[72:73], 0
	v_mov_b64_e32 v[74:75], 0
	v_mov_b64_e32 v[76:77], 0
	v_mov_b64_e32 v[78:79], 0
	v_mov_b64_e32 v[80:81], 0
	v_mov_b64_e32 v[82:83], 0
	v_mov_b64_e32 v[84:85], 0
	v_mov_b64_e32 v[86:87], 0
	v_mov_b64_e32 v[88:89], 0
	v_mov_b64_e32 v[90:91], 0
	v_mov_b64_e32 v[92:93], 0
	v_mov_b64_e32 v[94:95], 0
	v_mov_b64_e32 v[96:97], 0
	v_mov_b64_e32 v[98:99], 0
	v_mov_b64_e32 v[100:101], 0
	v_mov_b64_e32 v[102:103], 0
	v_mov_b64_e32 v[104:105], 0
	v_mov_b64_e32 v[106:107], 0
	v_mov_b64_e32 v[108:109], 0
	v_mov_b64_e32 v[110:111], 0
	v_mov_b64_e32 v[112:113], 0
	v_mov_b64_e32 v[114:115], 0
	v_mov_b64_e32 v[116:117], 0
	v_mov_b64_e32 v[118:119], 0
	v_mov_b64_e32 v[120:121], 0
	v_mov_b64_e32 v[122:123], 0
	v_mov_b64_e32 v[124:125], 0
	v_mov_b64_e32 v[126:127], 0

.LBB0_1682:
	s_ashr_i32 s35, s34, 31
	s_lshl_b64 s[36:37], s[34:35], 20
	s_add_u32 s36, s60, s36
	s_addc_u32 s37, s61, s37
	s_and_b64 s[38:39], s[10:11], exec
	s_cselect_b32 s1, s37, s43
	s_cselect_b32 s35, s36, s42
	s_ashr_i32 s31, s30, 31
	s_lshl_b64 s[38:39], s[30:31], 20
	s_add_u32 s38, s96, s38
	s_addc_u32 s39, s97, s39
	s_and_b64 s[46:47], s[10:11], exec
	s_cselect_b32 s31, s39, s45
	s_cselect_b32 s41, s38, s44
	s_add_u32 s42, s42, 0x80080
	s_addc_u32 s43, s43, 0
	s_add_u32 s65, s44, 0x100
	s_addc_u32 s66, s45, 0
	s_mov_b32 s67, -2
	s_waitcnt lgkmcnt(0)
	s_waitcnt vmcnt(0)
	v_mov_b64_e32 v[0:1], 0
	v_mov_b64_e32 v[2:3], 0
	v_mov_b64_e32 v[4:5], 0
	v_mov_b64_e32 v[6:7], 0
	v_mov_b64_e32 v[8:9], 0
	v_mov_b64_e32 v[10:11], 0
	v_mov_b64_e32 v[12:13], 0
	v_mov_b64_e32 v[14:15], 0
	v_mov_b64_e32 v[16:17], 0
	v_mov_b64_e32 v[18:19], 0
	v_mov_b64_e32 v[20:21], 0
	v_mov_b64_e32 v[22:23], 0
	v_mov_b64_e32 v[24:25], 0
	v_mov_b64_e32 v[26:27], 0
	v_mov_b64_e32 v[28:29], 0
	v_mov_b64_e32 v[30:31], 0
	v_mov_b64_e32 v[32:33], 0
	v_mov_b64_e32 v[34:35], 0
	v_mov_b64_e32 v[36:37], 0
	v_mov_b64_e32 v[38:39], 0
	v_mov_b64_e32 v[40:41], 0
	v_mov_b64_e32 v[42:43], 0
	v_mov_b64_e32 v[44:45], 0
	v_mov_b64_e32 v[46:47], 0
	v_mov_b64_e32 v[48:49], 0
	v_mov_b64_e32 v[50:51], 0
	v_mov_b64_e32 v[52:53], 0
	v_mov_b64_e32 v[54:55], 0
	v_mov_b64_e32 v[56:57], 0
	v_mov_b64_e32 v[58:59], 0
	v_mov_b64_e32 v[60:61], 0
	v_mov_b64_e32 v[62:63], 0
	v_mov_b64_e32 v[64:65], 0
	v_mov_b64_e32 v[66:67], 0
	v_mov_b64_e32 v[68:69], 0
	v_mov_b64_e32 v[70:71], 0
	v_mov_b64_e32 v[72:73], 0
	v_mov_b64_e32 v[74:75], 0
	v_mov_b64_e32 v[76:77], 0
	v_mov_b64_e32 v[78:79], 0
	v_mov_b64_e32 v[80:81], 0
	v_mov_b64_e32 v[82:83], 0
	v_mov_b64_e32 v[84:85], 0
	v_mov_b64_e32 v[86:87], 0
	v_mov_b64_e32 v[88:89], 0
	v_mov_b64_e32 v[90:91], 0
	v_mov_b64_e32 v[92:93], 0
	v_mov_b64_e32 v[94:95], 0
	v_mov_b64_e32 v[96:97], 0
	v_mov_b64_e32 v[98:99], 0
	v_mov_b64_e32 v[100:101], 0
	v_mov_b64_e32 v[102:103], 0
	v_mov_b64_e32 v[104:105], 0
	v_mov_b64_e32 v[106:107], 0
	v_mov_b64_e32 v[108:109], 0
	v_mov_b64_e32 v[110:111], 0
	v_mov_b64_e32 v[112:113], 0
	v_mov_b64_e32 v[114:115], 0
	v_mov_b64_e32 v[116:117], 0
	v_mov_b64_e32 v[118:119], 0
	v_mov_b64_e32 v[120:121], 0
	v_mov_b64_e32 v[122:123], 0
	v_mov_b64_e32 v[124:125], 0
	v_mov_b64_e32 v[126:127], 0

.LBB0_1776:
	s_ashr_i32 s19, s18, 31
	s_lshl_b64 s[28:29], s[18:19], 20
	s_add_u32 s28, s72, s28
	s_addc_u32 s29, s73, s29
	s_and_b64 s[30:31], s[4:5], exec
	s_cselect_b32 s19, s29, s35
	s_cselect_b32 s56, s28, s34
	s_ashr_i32 s17, s16, 31
	s_lshl_b64 s[30:31], s[16:17], 20
	s_add_u32 s30, s78, s30
	s_addc_u32 s31, s79, s31
	s_and_b64 s[38:39], s[4:5], exec
	s_cselect_b32 s17, s31, s37
	s_cselect_b32 s57, s30, s36
	s_add_u32 s34, s34, 0x80080
	s_addc_u32 s35, s35, 0
	s_add_u32 s58, s36, 0x100
	s_addc_u32 s59, s37, 0
	s_mov_b32 s62, -2
	s_waitcnt vmcnt(0)
	v_mov_b64_e32 v[0:1], 0
	v_mov_b64_e32 v[2:3], 0
	v_mov_b64_e32 v[4:5], 0
	v_mov_b64_e32 v[6:7], 0
	v_mov_b64_e32 v[8:9], 0
	v_mov_b64_e32 v[10:11], 0
	v_mov_b64_e32 v[12:13], 0
	v_mov_b64_e32 v[14:15], 0
	v_mov_b64_e32 v[16:17], 0
	v_mov_b64_e32 v[18:19], 0
	v_mov_b64_e32 v[20:21], 0
	v_mov_b64_e32 v[22:23], 0
	v_mov_b64_e32 v[24:25], 0
	v_mov_b64_e32 v[26:27], 0
	v_mov_b64_e32 v[28:29], 0
	v_mov_b64_e32 v[30:31], 0
	v_mov_b64_e32 v[32:33], 0
	v_mov_b64_e32 v[34:35], 0
	v_mov_b64_e32 v[36:37], 0
	v_mov_b64_e32 v[38:39], 0
	v_mov_b64_e32 v[40:41], 0
	v_mov_b64_e32 v[42:43], 0
	v_mov_b64_e32 v[44:45], 0
	v_mov_b64_e32 v[46:47], 0
	v_mov_b64_e32 v[48:49], 0
	v_mov_b64_e32 v[50:51], 0
	v_mov_b64_e32 v[52:53], 0
	v_mov_b64_e32 v[54:55], 0
	v_mov_b64_e32 v[56:57], 0
	v_mov_b64_e32 v[58:59], 0
	v_mov_b64_e32 v[60:61], 0
	v_mov_b64_e32 v[62:63], 0
	v_mov_b64_e32 v[64:65], 0
	v_mov_b64_e32 v[66:67], 0
	v_mov_b64_e32 v[68:69], 0
	v_mov_b64_e32 v[70:71], 0
	v_mov_b64_e32 v[72:73], 0
	v_mov_b64_e32 v[74:75], 0
	v_mov_b64_e32 v[76:77], 0
	v_mov_b64_e32 v[78:79], 0
	v_mov_b64_e32 v[80:81], 0
	v_mov_b64_e32 v[82:83], 0
	v_mov_b64_e32 v[84:85], 0
	v_mov_b64_e32 v[86:87], 0
	v_mov_b64_e32 v[88:89], 0
	v_mov_b64_e32 v[90:91], 0
	v_mov_b64_e32 v[92:93], 0
	v_mov_b64_e32 v[94:95], 0
	v_mov_b64_e32 v[96:97], 0
	v_mov_b64_e32 v[98:99], 0
	v_mov_b64_e32 v[100:101], 0
	v_mov_b64_e32 v[102:103], 0
	v_mov_b64_e32 v[104:105], 0
	v_mov_b64_e32 v[106:107], 0
	v_mov_b64_e32 v[108:109], 0
	v_mov_b64_e32 v[110:111], 0
	v_mov_b64_e32 v[112:113], 0
	v_mov_b64_e32 v[114:115], 0
	v_mov_b64_e32 v[116:117], 0
	v_mov_b64_e32 v[118:119], 0
	v_mov_b64_e32 v[120:121], 0
	v_mov_b64_e32 v[122:123], 0
	v_mov_b64_e32 v[124:125], 0
	v_mov_b64_e32 v[126:127], 0

.LBB0_1911:
	s_ashr_i32 s29, s28, 31
	s_lshl_b64 s[30:31], s[28:29], 20
	s_add_u32 s30, s60, s30
	s_addc_u32 s31, s61, s31
	s_and_b64 s[34:35], s[10:11], exec
	s_cselect_b32 s1, s31, s39
	s_cselect_b32 s29, s30, s38
	s_ashr_i32 s21, s20, 31
	s_lshl_b64 s[34:35], s[20:21], 20
	v_readlane_b32 s22, v244, 61
	v_readlane_b32 s23, v244, 62
	s_add_u32 s34, s22, s34
	s_addc_u32 s35, s23, s35
	s_and_b64 s[42:43], s[10:11], exec
	s_cselect_b32 s21, s35, s41
	s_cselect_b32 s37, s34, s40
	s_add_u32 s38, s38, 0x80080
	s_addc_u32 s39, s39, 0
	s_add_u32 s59, s40, 0x100
	s_addc_u32 s62, s41, 0
	s_mov_b32 s63, -2
	s_waitcnt lgkmcnt(0)
	s_waitcnt vmcnt(0)
	v_mov_b64_e32 v[0:1], 0
	v_mov_b64_e32 v[2:3], 0
	v_mov_b64_e32 v[4:5], 0
	v_mov_b64_e32 v[6:7], 0
	v_mov_b64_e32 v[8:9], 0
	v_mov_b64_e32 v[10:11], 0
	v_mov_b64_e32 v[12:13], 0
	v_mov_b64_e32 v[14:15], 0
	v_mov_b64_e32 v[16:17], 0
	v_mov_b64_e32 v[18:19], 0
	v_mov_b64_e32 v[20:21], 0
	v_mov_b64_e32 v[22:23], 0
	v_mov_b64_e32 v[24:25], 0
	v_mov_b64_e32 v[26:27], 0
	v_mov_b64_e32 v[28:29], 0
	v_mov_b64_e32 v[30:31], 0
	v_mov_b64_e32 v[32:33], 0
	v_mov_b64_e32 v[34:35], 0
	v_mov_b64_e32 v[36:37], 0
	v_mov_b64_e32 v[38:39], 0
	v_mov_b64_e32 v[40:41], 0
	v_mov_b64_e32 v[42:43], 0
	v_mov_b64_e32 v[44:45], 0
	v_mov_b64_e32 v[46:47], 0
	v_mov_b64_e32 v[48:49], 0
	v_mov_b64_e32 v[50:51], 0
	v_mov_b64_e32 v[52:53], 0
	v_mov_b64_e32 v[54:55], 0
	v_mov_b64_e32 v[56:57], 0
	v_mov_b64_e32 v[58:59], 0
	v_mov_b64_e32 v[60:61], 0
	v_mov_b64_e32 v[62:63], 0
	v_mov_b64_e32 v[64:65], 0
	v_mov_b64_e32 v[66:67], 0
	v_mov_b64_e32 v[68:69], 0
	v_mov_b64_e32 v[70:71], 0
	v_mov_b64_e32 v[72:73], 0
	v_mov_b64_e32 v[74:75], 0
	v_mov_b64_e32 v[76:77], 0
	v_mov_b64_e32 v[78:79], 0
	v_mov_b64_e32 v[80:81], 0
	v_mov_b64_e32 v[82:83], 0
	v_mov_b64_e32 v[84:85], 0
	v_mov_b64_e32 v[86:87], 0
	v_mov_b64_e32 v[88:89], 0
	v_mov_b64_e32 v[90:91], 0
	v_mov_b64_e32 v[92:93], 0
	v_mov_b64_e32 v[94:95], 0
	v_mov_b64_e32 v[96:97], 0
	v_mov_b64_e32 v[98:99], 0
	v_mov_b64_e32 v[100:101], 0
	v_mov_b64_e32 v[102:103], 0
	v_mov_b64_e32 v[104:105], 0
	v_mov_b64_e32 v[106:107], 0
	v_mov_b64_e32 v[108:109], 0
	v_mov_b64_e32 v[110:111], 0
	v_mov_b64_e32 v[112:113], 0
	v_mov_b64_e32 v[114:115], 0
	v_mov_b64_e32 v[116:117], 0
	v_mov_b64_e32 v[118:119], 0
	v_mov_b64_e32 v[120:121], 0
	v_mov_b64_e32 v[122:123], 0
	v_mov_b64_e32 v[124:125], 0
	v_mov_b64_e32 v[126:127], 0

.LBB0_1997:
	s_ashr_i32 s17, s16, 31
	s_lshl_b64 s[18:19], s[16:17], 20
	s_add_u32 s18, s72, s18
	s_addc_u32 s19, s73, s19
	s_and_b64 s[20:21], s[4:5], exec
	s_cselect_b32 s17, s19, s23
	s_cselect_b32 s52, s18, s22
	s_ashr_i32 s15, s14, 31
	s_lshl_b64 s[20:21], s[14:15], 20
	s_add_u32 s20, s24, s20
	s_addc_u32 s21, s25, s21
	s_and_b64 s[30:31], s[4:5], exec
	s_cselect_b32 s15, s21, s29
	s_cselect_b32 s53, s20, s28
	s_add_u32 s22, s22, 0x80080
	s_addc_u32 s23, s23, 0
	s_add_u32 s54, s28, 0x100
	s_addc_u32 s55, s29, 0
	s_mov_b32 s56, -2
	s_waitcnt vmcnt(0)
	v_mov_b64_e32 v[0:1], 0
	v_mov_b64_e32 v[2:3], 0
	v_mov_b64_e32 v[4:5], 0
	v_mov_b64_e32 v[6:7], 0
	v_mov_b64_e32 v[8:9], 0
	v_mov_b64_e32 v[10:11], 0
	v_mov_b64_e32 v[12:13], 0
	v_mov_b64_e32 v[14:15], 0
	v_mov_b64_e32 v[16:17], 0
	v_mov_b64_e32 v[18:19], 0
	v_mov_b64_e32 v[20:21], 0
	v_mov_b64_e32 v[22:23], 0
	v_mov_b64_e32 v[24:25], 0
	v_mov_b64_e32 v[26:27], 0
	v_mov_b64_e32 v[28:29], 0
	v_mov_b64_e32 v[30:31], 0
	v_mov_b64_e32 v[32:33], 0
	v_mov_b64_e32 v[34:35], 0
	v_mov_b64_e32 v[36:37], 0
	v_mov_b64_e32 v[38:39], 0
	v_mov_b64_e32 v[40:41], 0
	v_mov_b64_e32 v[42:43], 0
	v_mov_b64_e32 v[44:45], 0
	v_mov_b64_e32 v[46:47], 0
	v_mov_b64_e32 v[48:49], 0
	v_mov_b64_e32 v[50:51], 0
	v_mov_b64_e32 v[52:53], 0
	v_mov_b64_e32 v[54:55], 0
	v_mov_b64_e32 v[56:57], 0
	v_mov_b64_e32 v[58:59], 0
	v_mov_b64_e32 v[60:61], 0
	v_mov_b64_e32 v[62:63], 0
	v_mov_b64_e32 v[64:65], 0
	v_mov_b64_e32 v[66:67], 0
	v_mov_b64_e32 v[68:69], 0
	v_mov_b64_e32 v[70:71], 0
	v_mov_b64_e32 v[72:73], 0
	v_mov_b64_e32 v[74:75], 0
	v_mov_b64_e32 v[76:77], 0
	v_mov_b64_e32 v[78:79], 0
	v_mov_b64_e32 v[80:81], 0
	v_mov_b64_e32 v[82:83], 0
	v_mov_b64_e32 v[84:85], 0
	v_mov_b64_e32 v[86:87], 0
	v_mov_b64_e32 v[88:89], 0
	v_mov_b64_e32 v[90:91], 0
	v_mov_b64_e32 v[92:93], 0
	v_mov_b64_e32 v[94:95], 0
	v_mov_b64_e32 v[96:97], 0
	v_mov_b64_e32 v[98:99], 0
	v_mov_b64_e32 v[100:101], 0
	v_mov_b64_e32 v[102:103], 0
	v_mov_b64_e32 v[104:105], 0
	v_mov_b64_e32 v[106:107], 0
	v_mov_b64_e32 v[108:109], 0
	v_mov_b64_e32 v[110:111], 0
	v_mov_b64_e32 v[112:113], 0
	v_mov_b64_e32 v[114:115], 0
	v_mov_b64_e32 v[116:117], 0
	v_mov_b64_e32 v[118:119], 0
	v_mov_b64_e32 v[120:121], 0
	v_mov_b64_e32 v[122:123], 0
	v_mov_b64_e32 v[124:125], 0
	v_mov_b64_e32 v[126:127], 0

.LBB0_2077:
	s_add_u32 s43, s16, 0x100
	s_addc_u32 s44, s17, 0
	s_mov_b32 s45, -2
	s_waitcnt vmcnt(0)
	v_mov_b64_e32 v[0:1], 0
	v_mov_b64_e32 v[2:3], 0
	v_mov_b64_e32 v[4:5], 0
	v_mov_b64_e32 v[6:7], 0
	v_mov_b64_e32 v[8:9], 0
	v_mov_b64_e32 v[10:11], 0
	v_mov_b64_e32 v[12:13], 0
	v_mov_b64_e32 v[14:15], 0
	v_mov_b64_e32 v[16:17], 0
	v_mov_b64_e32 v[18:19], 0
	v_mov_b64_e32 v[20:21], 0
	v_mov_b64_e32 v[22:23], 0
	v_mov_b64_e32 v[24:25], 0
	v_mov_b64_e32 v[26:27], 0
	v_mov_b64_e32 v[28:29], 0
	v_mov_b64_e32 v[30:31], 0
	v_mov_b64_e32 v[32:33], 0
	v_mov_b64_e32 v[34:35], 0
	v_mov_b64_e32 v[36:37], 0
	v_mov_b64_e32 v[38:39], 0
	v_mov_b64_e32 v[40:41], 0
	v_mov_b64_e32 v[42:43], 0
	v_mov_b64_e32 v[44:45], 0
	v_mov_b64_e32 v[46:47], 0
	v_mov_b64_e32 v[48:49], 0
	v_mov_b64_e32 v[50:51], 0
	v_mov_b64_e32 v[52:53], 0
	v_mov_b64_e32 v[54:55], 0
	v_mov_b64_e32 v[56:57], 0
	v_mov_b64_e32 v[58:59], 0
	v_mov_b64_e32 v[60:61], 0
	v_mov_b64_e32 v[62:63], 0
	v_mov_b64_e32 v[64:65], 0
	v_mov_b64_e32 v[66:67], 0
	v_mov_b64_e32 v[68:69], 0
	v_mov_b64_e32 v[70:71], 0
	v_mov_b64_e32 v[72:73], 0
	v_mov_b64_e32 v[74:75], 0
	v_mov_b64_e32 v[76:77], 0
	v_mov_b64_e32 v[78:79], 0
	v_mov_b64_e32 v[80:81], 0
	v_mov_b64_e32 v[82:83], 0
	v_mov_b64_e32 v[84:85], 0
	v_mov_b64_e32 v[86:87], 0
	v_mov_b64_e32 v[88:89], 0
	v_mov_b64_e32 v[90:91], 0
	v_mov_b64_e32 v[92:93], 0
	v_mov_b64_e32 v[94:95], 0
	v_mov_b64_e32 v[96:97], 0
	v_mov_b64_e32 v[98:99], 0
	v_mov_b64_e32 v[100:101], 0
	v_mov_b64_e32 v[102:103], 0
	v_mov_b64_e32 v[104:105], 0
	v_mov_b64_e32 v[106:107], 0
	v_mov_b64_e32 v[108:109], 0
	v_mov_b64_e32 v[110:111], 0
	v_mov_b64_e32 v[112:113], 0
	v_mov_b64_e32 v[114:115], 0
	v_mov_b64_e32 v[116:117], 0
	v_mov_b64_e32 v[118:119], 0
	v_mov_b64_e32 v[120:121], 0
	v_mov_b64_e32 v[122:123], 0
	v_mov_b64_e32 v[124:125], 0
	v_mov_b64_e32 v[126:127], 0
